# DSA phase rewritten: dense masked attention per (batch,kv-head,64-query chunk), K/V 64-key tiles shared via LDS by 8 waves, selection as bitmask, no-max softmax; same bf16 MFMA/f32 math
# speedup vs baseline: 1.0577x; 1.0577x over previous
; #define LAS __attribute__((address_space(3)))
; #define LDS_WAIT() asm volatile("s_waitcnt lgkmcnt(0)" ::: "memory")
; #define PH_BEGIN if (ph >= lo && ph < hi) { int lane = __builtin_amdgcn_mbcnt_hi(~0u, __builtin_amdgcn_mbcnt_lo(~0u, 0u)); asm volatile("" : "+v"(lane));
; __device__ __forceinline__ void dsa_unit(const bf16* QB, const int* SEL, bf16* AO, int b, int kvh, int t, LAS unsigned char* wl, int lane) {
;     const size_t rowbase = (size_t)b * SEQ, row = rowbase + t;
;     const int n = lane & 31, hi = lane >> 5, l15 = lane & 15, kq = lane >> 4;
;     const int ce = ((t >> 6) + 1) << 6; const int nsel = ce < 256 ? ce : 256;
;     LAS unsigned char* buf = wl;
;     LAS bf16* pT = (LAS bf16*)(wl + 9216);
;     LAS int* il = (LAS int*)(wl + 11264);
;     const LAS float* bl = (const LAS float*)(wl + 12288) + kvh * 128;
;     int sidx[8];
; #pragma unroll
;     for (int kb = 0; kb < 8; ++kb) { const int p = 32 * kb + n; sidx[kb] = (p < nsel) ? SEL[row * 256 + p] : 0; }
;     bf16x8 qf[4];
;     { const bf16* qp = QB + row * NBP + CQ + (kvh * 4 + (l15 & 3)) * 128 + 8 * kq;
; #pragma unroll
;       for (int ks = 0; ks < 4; ++ks) qf[ks] = *(const bf16x8*)(qp + 32 * ks); }
;     if (hi == 0) {
; #pragma unroll
;         for (int kb = 0; kb < 8; ++kb) il[32 * kb + n] = sidx[kb];
;     }
;     LDS_WAIT();
;     const int r4 = kq, c16 = l15;
;     const bf16* kg = QB + rowbase * NBP + CK + kvh * 128 + c16 * 8;
;     const bf16* vg = QB + rowbase * NBP + CV + kvh * 128 + c16 * 8;
; __global__ void __launch_bounds__(NWAVES * 64, 2) fwd_megakernel(Args args) {
;     ...
;             PH_BEGIN
;             {
;                 { LAS float* blw = (LAS float*)(wl + 12288);
; #pragma unroll
;                   for (int i = 0; i < 8; ++i) blw[lane + 64 * i] = LOG2E * args.in[I_RELB][lane + 64 * i];
;                   LDS_WAIT(); }
;                 for (int rep = 0; rep < REP_DSA; ++rep)
;                 if ((G & 7) == 0) { const int x = blockIdx.x & 7; const int nxw = (G >> 3) * NWAVES; const int wx = (blockIdx.x >> 3) * NWAVES + wave;
;                     for (int i = wx; i < 2 * SEQ; i += nxw) { const int combo = x + 8 * (i / SEQ);
;     ...
;  dsa_unit(QKV, SEL, AO, combo >> 2, combo & 3, i % SEQ, wl, lane);
;     ...
;  } }
.LBB0_601:
	s_andn2_b64 vcc, exec, s[0:1]
	s_cbranch_vccnz .LBB0_1030
	s_branch .Ldsa_new
.Ldsa_new:
	v_readfirstlane_b32 s0, v207
	v_readlane_b32 s1, v251, 14
	v_readlane_b32 s12, v251, 0
	v_readlane_b32 s13, v251, 1
	s_lshr_b32 s0, s0, 6
	s_lshr_b32 s2, s84, 3
	s_mov_b32 s16, 0x88000
	s_mov_b32 s17, 0
	s_movk_i32 s23, 0x2200
	v_lshlrev_b32_e32 v178, 2, v207
	s_nop 4
	global_load_dword v179, v178, s[12:13]
	v_and_b32_e32 v64, 31, v206
	v_lshrrev_b32_e32 v65, 5, v206
	v_lshlrev_b32_e32 v175, 3, v65
	v_and_b32_e32 v66, 19, v64
	v_lshrrev_b32_e32 v67, 1, v64
	v_and_b32_e32 v67, 4, v67
	v_lshlrev_b32_e32 v68, 1, v64
	v_and_b32_e32 v68, 8, v68
	v_or3_b32 v66, v66, v67, v68
	v_mul_u32_u24_e32 v66, 0x110, v66
	v_lshl_add_u32 v66, v65, 4, v66
	v_add_u32_e32 v164, 0x4800, v66
	v_bfe_u32 v66, v206, 2, 2
	v_or_b32_e32 v66, v175, v66
	v_mul_u32_u24_e32 v66, 0x120, v66
	v_and_b32_e32 v67, 16, v206
	v_and_b32_e32 v68, 3, v206
	v_lshl_or_b32 v67, v68, 2, v67
	v_lshl_add_u32 v165, v67, 1, v66
	v_lshrrev_b32_e32 v66, 4, v207
	v_and_b32_e32 v67, 15, v207
	v_lshlrev_b32_e32 v67, 4, v67
	v_mul_u32_u24_e32 v68, 0x110, v66
	v_add_u32_e32 v68, v68, v67
	v_add_u32_e32 v166, 0x4800, v68
	v_mul_u32_u24_e32 v68, 0x120, v66
	v_add_u32_e32 v167, v68, v67
	s_waitcnt vmcnt(0)
	v_mul_f32_e32 v179, 0x3fb8aa3b, v179
	v_add_u32_e32 v178, 0x19800, v178
	ds_write_b32 v178, v179
	s_mov_b32 s3, s1
.Ldsa_unit:
	s_cmpk_ge_u32 s3, 0x200
	s_cbranch_scc1 .Ldsa_done
	s_and_b32 s24, s3, 7
	s_lshr_b32 s25, s3, 3
	s_and_b32 s35, s25, 31
	s_lshr_b32 s25, s25, 5
	s_lshl_b32 s25, s25, 3
	s_add_u32 s24, s24, s25
	s_lshr_b32 s4, s24, 2
	s_lshl_b32 s4, s4, 12
	s_and_b32 s5, s24, 3
	s_mov_b32 s21, 0
.Ldsa_half:
	s_sub_u32 s6, 63, s35
	s_cmp_eq_u32 s21, 0
	s_cselect_b32 s6, s6, s35
	s_lshl_b32 s7, s6, 6
	s_add_u32 s8, s6, 1
	s_lshl_b32 s18, s8, 6
	s_min_u32 s18, s18, 0x100
	v_mov_b32_e32 v64, 0
	v_mov_b32_e32 v65, 0
	v_mov_b32_e32 v66, 0
	v_mov_b32_e32 v67, 0
	v_lshlrev_b32_e32 v178, 6, v207
	v_add_u32_e32 v178, 0x11800, v178
	ds_write_b128 v178, v[64:67] offset:0
	ds_write_b128 v178, v[64:67] offset:16
	ds_write_b128 v178, v[64:67] offset:32
	ds_write_b128 v178, v[64:67] offset:48
	v_lshrrev_b32_e32 v178, 4, v207
	v_add_u32_e32 v178, s4, v178
	v_and_b32_e32 v179, 15, v207
	v_lshlrev_b32_e32 v182, 4, v179
	s_lshl_b32 s24, s5, 8
	s_add_u32 s24, s24, 0x1000
	v_add_u32_e32 v182, s24, v182
	v_lshl_add_u64 v[160:161], s[78:79], 0, v[182:183]
	v_mad_u64_u32 v[160:161], s[12:13], v178, s23, v[160:161]
	s_mov_b32 s24, 0x44000
	s_mov_b32 s25, 0
	v_lshl_add_u64 v[162:163], v[160:161], 0, s[24:25]
	global_load_dwordx4 v[144:147], v[160:161], off
	global_load_dwordx4 v[148:151], v[160:161], off offset:1024
	global_load_dwordx4 v[152:155], v[162:163], off
	global_load_dwordx4 v[156:159], v[162:163], off offset:1024
	v_lshl_add_u64 v[160:161], v[160:161], 0, s[16:17]
	v_lshl_add_u64 v[162:163], v[162:163], 0, s[16:17]
	v_and_b32_e32 v64, 31, v206
	v_lshrrev_b32_e32 v65, 2, v64
	v_and_b32_e32 v66, 3, v64
	s_lshl_b32 s24, s0, 3
	s_add_u32 s24, s24, s7
	s_add_u32 s24, s24, s4
	v_add_u32_e32 v178, s24, v65
	s_lshl_b32 s25, s5, 2
	v_add_u32_e32 v179, s25, v66
	v_lshlrev_b32_e32 v179, 8, v179
	v_lshl_add_u32 v182, v175, 1, v179
	v_lshl_add_u64 v[128:129], s[78:79], 0, v[182:183]
	v_mad_u64_u32 v[128:129], s[12:13], v178, s23, v[128:129]
	global_load_dwordx4 v[80:83], v[128:129], off offset:0
	global_load_dwordx4 v[84:87], v[128:129], off offset:32
	global_load_dwordx4 v[88:91], v[128:129], off offset:64
	global_load_dwordx4 v[92:95], v[128:129], off offset:96
	global_load_dwordx4 v[96:99], v[128:129], off offset:128
	global_load_dwordx4 v[100:103], v[128:129], off offset:160
	global_load_dwordx4 v[104:107], v[128:129], off offset:192
	global_load_dwordx4 v[108:111], v[128:129], off offset:224
	s_lshl_b32 s24, s0, 3
	v_add_u32_e32 v178, s24, v65
	v_lshlrev_b32_e32 v172, 9, v178
	v_add_u32_e32 v172, 0x11800, v172
	s_add_u32 s24, s24, s7
	v_add_u32_e32 v178, s24, v65
	v_sub_u32_e32 v178, v175, v178
	v_add_u32_e32 v178, 0x80, v178
	v_lshlrev_b32_e32 v178, 2, v178
	v_lshl_add_u32 v177, v66, 10, v178
	v_add_u32_e32 v177, 0x1a400, v177
	s_sub_u32 s19, s24, 0x7a
	s_lshl_b32 s25, s5, 2
	v_add_u32_e32 v178, s25, v66
	v_lshlrev_b32_e32 v178, 7, v178
	v_add_u32_e32 v176, 0x1983c, v178
	s_waitcnt lgkmcnt(0)
	s_barrier
; #define LAS __attribute__((address_space(3)))
; __device__ __forceinline__ int t5_bucket(int rel) {
;     const int nabs = rel < 0 ? -rel : rel;
;     int bk = nabs;
;     if (nabs >= 8) bk = 8 + (nabs >= 12) + (nabs >= 16) + (nabs >= 23) + (nabs >= 32) + (nabs >= 46) + (nabs >= 64) + (nabs >= 91);
;     return bk + (rel > 0 ? 16 : 0);
; }
; __device__ __forceinline__ void dsa_unit(const bf16* QB, const int* SEL, bf16* AO, int b, int kvh, int t, LAS unsigned char* wl, int lane) {
;     const size_t rowbase = (size_t)b * SEQ, row = rowbase + t;
;     const int n = lane & 31, hi = lane >> 5, l15 = lane & 15, kq = lane >> 4;
;     const int ce = ((t >> 6) + 1) << 6; const int nsel = ce < 256 ? ce : 256;
;     LAS unsigned char* buf = wl;
;     LAS bf16* pT = (LAS bf16*)(wl + 9216);
;     LAS int* il = (LAS int*)(wl + 11264);
;     const LAS float* bl = (const LAS float*)(wl + 12288) + kvh * 128;
;     int sidx[8];
; #pragma unroll
;     for (int kb = 0; kb < 8; ++kb) { const int p = 32 * kb + n; sidx[kb] = (p < nsel) ? SEL[row * 256 + p] : 0; }
	ds_read_b32 v176, v176
	v_and_b32_e32 v64, 0xff, v207
	v_subrev_u32_e32 v65, 0x80, v64
	v_sub_u32_e32 v66, 0, v65
	v_max_i32_e32 v66, v65, v66
	v_mov_b32_e32 v67, 8
	v_cmp_le_i32_e32 vcc, 12, v66
	s_nop 1
	v_addc_co_u32_e32 v67, vcc, 0, v67, vcc
	v_cmp_le_i32_e32 vcc, 16, v66
	s_nop 1
	v_addc_co_u32_e32 v67, vcc, 0, v67, vcc
	v_cmp_le_i32_e32 vcc, 23, v66
	s_nop 1
	v_addc_co_u32_e32 v67, vcc, 0, v67, vcc
	v_cmp_le_i32_e32 vcc, 32, v66
	s_nop 1
	v_addc_co_u32_e32 v67, vcc, 0, v67, vcc
	v_cmp_le_i32_e32 vcc, 46, v66
	s_nop 1
	v_addc_co_u32_e32 v67, vcc, 0, v67, vcc
	v_cmp_le_i32_e32 vcc, 64, v66
	s_nop 1
	v_addc_co_u32_e32 v67, vcc, 0, v67, vcc
	v_cmp_le_i32_e32 vcc, 91, v66
	s_nop 1
	v_addc_co_u32_e32 v67, vcc, 0, v67, vcc
	v_cmp_gt_i32_e32 vcc, 8, v66
	s_nop 1
	v_cndmask_b32_e32 v67, v67, v66, vcc
	v_add_u32_e32 v68, 16, v67
	v_cmp_lt_i32_e32 vcc, 0, v65
	s_nop 1
	v_cndmask_b32_e32 v67, v67, v68, vcc
	v_lshrrev_b32_e32 v68, 8, v207
	s_lshl_b32 s24, s5, 2
	v_add_u32_e32 v69, s24, v68
	v_lshl_add_u32 v69, v69, 5, v67
	v_lshlrev_b32_e32 v69, 2, v69
	v_add_u32_e32 v69, 0x19800, v69
	ds_read_b32 v70, v69
	ds_read_b32 v71, v69 offset:256
	v_lshl_add_u32 v72, v68, 8, v64
	v_lshlrev_b32_e32 v72, 2, v72
	v_add_u32_e32 v72, 0x1a400, v72
	s_waitcnt lgkmcnt(0)
	ds_write_b32 v72, v70
	ds_write_b32 v72, v71 offset:2048
	v_readlane_b32 s14, v251, 19
	v_readlane_b32 s15, v251, 20
	s_add_u32 s24, s4, s7
	s_lshl_b32 s24, s24, 10
	s_nop 3
	s_add_u32 s14, s14, s24
	s_addc_u32 s15, s15, 0
	v_lshlrev_b32_e32 v178, 2, v207
	v_and_b32_e32 v179, 0xff, v207
	v_cmp_gt_u32_e32 vcc, s18, v179
	s_and_saveexec_b64 s[40:41], vcc
	global_load_dword v0, v178, s[14:15]
	s_add_u32 s14, s14, 0x800
	s_addc_u32 s15, s15, 0
	global_load_dword v1, v178, s[14:15]
	s_add_u32 s14, s14, 0x800
	s_addc_u32 s15, s15, 0
	global_load_dword v2, v178, s[14:15]
	s_add_u32 s14, s14, 0x800
	s_addc_u32 s15, s15, 0
	global_load_dword v3, v178, s[14:15]
	s_add_u32 s14, s14, 0x800
	s_addc_u32 s15, s15, 0
	global_load_dword v4, v178, s[14:15]
	s_add_u32 s14, s14, 0x800
	s_addc_u32 s15, s15, 0
	global_load_dword v5, v178, s[14:15]
	s_add_u32 s14, s14, 0x800
	s_addc_u32 s15, s15, 0
	global_load_dword v6, v178, s[14:15]
	s_add_u32 s14, s14, 0x800
	s_addc_u32 s15, s15, 0
	global_load_dword v7, v178, s[14:15]
	s_add_u32 s14, s14, 0x800
	s_addc_u32 s15, s15, 0
	global_load_dword v8, v178, s[14:15]
	s_add_u32 s14, s14, 0x800
	s_addc_u32 s15, s15, 0
	global_load_dword v9, v178, s[14:15]
	s_add_u32 s14, s14, 0x800
	s_addc_u32 s15, s15, 0
	global_load_dword v10, v178, s[14:15]
	s_add_u32 s14, s14, 0x800
	s_addc_u32 s15, s15, 0
	global_load_dword v11, v178, s[14:15]
	s_add_u32 s14, s14, 0x800
	s_addc_u32 s15, s15, 0
	global_load_dword v12, v178, s[14:15]
	s_add_u32 s14, s14, 0x800
	s_addc_u32 s15, s15, 0
	global_load_dword v13, v178, s[14:15]
	s_add_u32 s14, s14, 0x800
	s_addc_u32 s15, s15, 0
	global_load_dword v14, v178, s[14:15]
	s_add_u32 s14, s14, 0x800
	s_addc_u32 s15, s15, 0
	global_load_dword v15, v178, s[14:15]
	s_add_u32 s14, s14, 0x800
	s_addc_u32 s15, s15, 0
	global_load_dword v16, v178, s[14:15]
	s_add_u32 s14, s14, 0x800
	s_addc_u32 s15, s15, 0
	global_load_dword v17, v178, s[14:15]
	s_add_u32 s14, s14, 0x800
	s_addc_u32 s15, s15, 0
	global_load_dword v18, v178, s[14:15]
	s_add_u32 s14, s14, 0x800
	s_addc_u32 s15, s15, 0
	global_load_dword v19, v178, s[14:15]
	s_add_u32 s14, s14, 0x800
	s_addc_u32 s15, s15, 0
	global_load_dword v20, v178, s[14:15]
	s_add_u32 s14, s14, 0x800
	s_addc_u32 s15, s15, 0
	global_load_dword v21, v178, s[14:15]
	s_add_u32 s14, s14, 0x800
	s_addc_u32 s15, s15, 0
	global_load_dword v22, v178, s[14:15]
	s_add_u32 s14, s14, 0x800
	s_addc_u32 s15, s15, 0
	global_load_dword v23, v178, s[14:15]
	s_add_u32 s14, s14, 0x800
	s_addc_u32 s15, s15, 0
	global_load_dword v24, v178, s[14:15]
	s_add_u32 s14, s14, 0x800
	s_addc_u32 s15, s15, 0
	global_load_dword v25, v178, s[14:15]
	s_add_u32 s14, s14, 0x800
	s_addc_u32 s15, s15, 0
	global_load_dword v26, v178, s[14:15]
	s_add_u32 s14, s14, 0x800
	s_addc_u32 s15, s15, 0
	global_load_dword v27, v178, s[14:15]
	s_add_u32 s14, s14, 0x800
	s_addc_u32 s15, s15, 0
	global_load_dword v28, v178, s[14:15]
	s_add_u32 s14, s14, 0x800
	s_addc_u32 s15, s15, 0
	global_load_dword v29, v178, s[14:15]
	s_add_u32 s14, s14, 0x800
	s_addc_u32 s15, s15, 0
	global_load_dword v30, v178, s[14:15]
	s_add_u32 s14, s14, 0x800
	s_addc_u32 s15, s15, 0
	global_load_dword v31, v178, s[14:15]
	v_lshrrev_b32_e32 v179, 8, v207
	v_lshlrev_b32_e32 v179, 9, v179
	v_add_u32_e32 v179, 0x11800, v179
	s_waitcnt vmcnt(31)
	v_lshrrev_b32_e32 v64, 3, v0
	v_and_b32_e32 v64, 0x1fc, v64
	v_add_u32_e32 v64, v179, v64
	v_lshlrev_b32_e64 v65, v0, 1
	ds_or_b32 v64, v65 offset:0
	s_waitcnt vmcnt(30)
	v_lshrrev_b32_e32 v64, 3, v1
	v_and_b32_e32 v64, 0x1fc, v64
	v_add_u32_e32 v64, v179, v64
	v_lshlrev_b32_e64 v65, v1, 1
	ds_or_b32 v64, v65 offset:1024
	s_waitcnt vmcnt(29)
	v_lshrrev_b32_e32 v64, 3, v2
	v_and_b32_e32 v64, 0x1fc, v64
	v_add_u32_e32 v64, v179, v64
	v_lshlrev_b32_e64 v65, v2, 1
	ds_or_b32 v64, v65 offset:2048
	s_waitcnt vmcnt(28)
	v_lshrrev_b32_e32 v64, 3, v3
	v_and_b32_e32 v64, 0x1fc, v64
	v_add_u32_e32 v64, v179, v64
	v_lshlrev_b32_e64 v65, v3, 1
	ds_or_b32 v64, v65 offset:3072
	s_waitcnt vmcnt(27)
	v_lshrrev_b32_e32 v64, 3, v4
	v_and_b32_e32 v64, 0x1fc, v64
	v_add_u32_e32 v64, v179, v64
	v_lshlrev_b32_e64 v65, v4, 1
	ds_or_b32 v64, v65 offset:4096
	s_waitcnt vmcnt(26)
	v_lshrrev_b32_e32 v64, 3, v5
	v_and_b32_e32 v64, 0x1fc, v64
	v_add_u32_e32 v64, v179, v64
	v_lshlrev_b32_e64 v65, v5, 1
	ds_or_b32 v64, v65 offset:5120
	s_waitcnt vmcnt(25)
; __device__ __forceinline__ void dsa_unit(const bf16* QB, const int* SEL, bf16* AO, int b, int kvh, int t, LAS unsigned char* wl, int lane) {
;     ...
;     int sidx[8];
; #pragma unroll
;     for (int kb = 0; kb < 8; ++kb) { const int p = 32 * kb + n; sidx[kb] = (p < nsel) ? SEL[row * 256 + p] : 0; }
;     bf16x8 qf[4];
;     { const bf16* qp = QB + row * NBP + CQ + (kvh * 4 + (l15 & 3)) * 128 + 8 * kq;
; #pragma unroll
;       for (int ks = 0; ks < 4; ++ks) qf[ks] = *(const bf16x8*)(qp + 32 * ks); }
;     if (hi == 0) {
; #pragma unroll
;         for (int kb = 0; kb < 8; ++kb) il[32 * kb + n] = sidx[kb];
;     }
	v_lshrrev_b32_e32 v64, 3, v6
	v_and_b32_e32 v64, 0x1fc, v64
	v_add_u32_e32 v64, v179, v64
	v_lshlrev_b32_e64 v65, v6, 1
	ds_or_b32 v64, v65 offset:6144
	s_waitcnt vmcnt(24)
	v_lshrrev_b32_e32 v64, 3, v7
	v_and_b32_e32 v64, 0x1fc, v64
	v_add_u32_e32 v64, v179, v64
	v_lshlrev_b32_e64 v65, v7, 1
	ds_or_b32 v64, v65 offset:7168
	s_waitcnt vmcnt(23)
	v_lshrrev_b32_e32 v64, 3, v8
	v_and_b32_e32 v64, 0x1fc, v64
	v_add_u32_e32 v64, v179, v64
	v_lshlrev_b32_e64 v65, v8, 1
	ds_or_b32 v64, v65 offset:8192
	s_waitcnt vmcnt(22)
	v_lshrrev_b32_e32 v64, 3, v9
	v_and_b32_e32 v64, 0x1fc, v64
	v_add_u32_e32 v64, v179, v64
	v_lshlrev_b32_e64 v65, v9, 1
	ds_or_b32 v64, v65 offset:9216
	s_waitcnt vmcnt(21)
	v_lshrrev_b32_e32 v64, 3, v10
	v_and_b32_e32 v64, 0x1fc, v64
	v_add_u32_e32 v64, v179, v64
	v_lshlrev_b32_e64 v65, v10, 1
	ds_or_b32 v64, v65 offset:10240
	s_waitcnt vmcnt(20)
	v_lshrrev_b32_e32 v64, 3, v11
	v_and_b32_e32 v64, 0x1fc, v64
	v_add_u32_e32 v64, v179, v64
	v_lshlrev_b32_e64 v65, v11, 1
	ds_or_b32 v64, v65 offset:11264
	s_waitcnt vmcnt(19)
	v_lshrrev_b32_e32 v64, 3, v12
	v_and_b32_e32 v64, 0x1fc, v64
	v_add_u32_e32 v64, v179, v64
	v_lshlrev_b32_e64 v65, v12, 1
	ds_or_b32 v64, v65 offset:12288
	s_waitcnt vmcnt(18)
	v_lshrrev_b32_e32 v64, 3, v13
	v_and_b32_e32 v64, 0x1fc, v64
	v_add_u32_e32 v64, v179, v64
	v_lshlrev_b32_e64 v65, v13, 1
	ds_or_b32 v64, v65 offset:13312
	s_waitcnt vmcnt(17)
	v_lshrrev_b32_e32 v64, 3, v14
	v_and_b32_e32 v64, 0x1fc, v64
	v_add_u32_e32 v64, v179, v64
	v_lshlrev_b32_e64 v65, v14, 1
	ds_or_b32 v64, v65 offset:14336
	s_waitcnt vmcnt(16)
	v_lshrrev_b32_e32 v64, 3, v15
	v_and_b32_e32 v64, 0x1fc, v64
	v_add_u32_e32 v64, v179, v64
	v_lshlrev_b32_e64 v65, v15, 1
	ds_or_b32 v64, v65 offset:15360
	s_waitcnt vmcnt(15)
	v_lshrrev_b32_e32 v64, 3, v16
	v_and_b32_e32 v64, 0x1fc, v64
	v_add_u32_e32 v64, v179, v64
	v_lshlrev_b32_e64 v65, v16, 1
	ds_or_b32 v64, v65 offset:16384
	s_waitcnt vmcnt(14)
	v_lshrrev_b32_e32 v64, 3, v17
	v_and_b32_e32 v64, 0x1fc, v64
	v_add_u32_e32 v64, v179, v64
	v_lshlrev_b32_e64 v65, v17, 1
	ds_or_b32 v64, v65 offset:17408
	s_waitcnt vmcnt(13)
	v_lshrrev_b32_e32 v64, 3, v18
	v_and_b32_e32 v64, 0x1fc, v64
	v_add_u32_e32 v64, v179, v64
	v_lshlrev_b32_e64 v65, v18, 1
	ds_or_b32 v64, v65 offset:18432
	s_waitcnt vmcnt(12)
	v_lshrrev_b32_e32 v64, 3, v19
	v_and_b32_e32 v64, 0x1fc, v64
	v_add_u32_e32 v64, v179, v64
	v_lshlrev_b32_e64 v65, v19, 1
	ds_or_b32 v64, v65 offset:19456
	s_waitcnt vmcnt(11)
	v_lshrrev_b32_e32 v64, 3, v20
	v_and_b32_e32 v64, 0x1fc, v64
	v_add_u32_e32 v64, v179, v64
	v_lshlrev_b32_e64 v65, v20, 1
	ds_or_b32 v64, v65 offset:20480
	s_waitcnt vmcnt(10)
	v_lshrrev_b32_e32 v64, 3, v21
	v_and_b32_e32 v64, 0x1fc, v64
	v_add_u32_e32 v64, v179, v64
	v_lshlrev_b32_e64 v65, v21, 1
	ds_or_b32 v64, v65 offset:21504
	s_waitcnt vmcnt(9)
	v_lshrrev_b32_e32 v64, 3, v22
	v_and_b32_e32 v64, 0x1fc, v64
	v_add_u32_e32 v64, v179, v64
	v_lshlrev_b32_e64 v65, v22, 1
	ds_or_b32 v64, v65 offset:22528
	s_waitcnt vmcnt(8)
	v_lshrrev_b32_e32 v64, 3, v23
	v_and_b32_e32 v64, 0x1fc, v64
	v_add_u32_e32 v64, v179, v64
	v_lshlrev_b32_e64 v65, v23, 1
	ds_or_b32 v64, v65 offset:23552
	s_waitcnt vmcnt(7)
	v_lshrrev_b32_e32 v64, 3, v24
	v_and_b32_e32 v64, 0x1fc, v64
	v_add_u32_e32 v64, v179, v64
	v_lshlrev_b32_e64 v65, v24, 1
	ds_or_b32 v64, v65 offset:24576
	s_waitcnt vmcnt(6)
	v_lshrrev_b32_e32 v64, 3, v25
	v_and_b32_e32 v64, 0x1fc, v64
	v_add_u32_e32 v64, v179, v64
	v_lshlrev_b32_e64 v65, v25, 1
	ds_or_b32 v64, v65 offset:25600
	s_waitcnt vmcnt(5)
	v_lshrrev_b32_e32 v64, 3, v26
	v_and_b32_e32 v64, 0x1fc, v64
	v_add_u32_e32 v64, v179, v64
	v_lshlrev_b32_e64 v65, v26, 1
	ds_or_b32 v64, v65 offset:26624
	s_waitcnt vmcnt(4)
	v_lshrrev_b32_e32 v64, 3, v27
	v_and_b32_e32 v64, 0x1fc, v64
	v_add_u32_e32 v64, v179, v64
	v_lshlrev_b32_e64 v65, v27, 1
	ds_or_b32 v64, v65 offset:27648
	s_waitcnt vmcnt(3)
	v_lshrrev_b32_e32 v64, 3, v28
	v_and_b32_e32 v64, 0x1fc, v64
	v_add_u32_e32 v64, v179, v64
	v_lshlrev_b32_e64 v65, v28, 1
	ds_or_b32 v64, v65 offset:28672
	s_waitcnt vmcnt(2)
	v_lshrrev_b32_e32 v64, 3, v29
	v_and_b32_e32 v64, 0x1fc, v64
	v_add_u32_e32 v64, v179, v64
	v_lshlrev_b32_e64 v65, v29, 1
	ds_or_b32 v64, v65 offset:29696
	s_waitcnt vmcnt(1)
	v_lshrrev_b32_e32 v64, 3, v30
	v_and_b32_e32 v64, 0x1fc, v64
	v_add_u32_e32 v64, v179, v64
	v_lshlrev_b32_e64 v65, v30, 1
	ds_or_b32 v64, v65 offset:30720
	s_waitcnt vmcnt(0)
	v_lshrrev_b32_e32 v64, 3, v31
	v_and_b32_e32 v64, 0x1fc, v64
	v_add_u32_e32 v64, v179, v64
	v_lshlrev_b32_e64 v65, v31, 1
	ds_or_b32 v64, v65 offset:31744
	s_mov_b64 exec, s[40:41]
	s_waitcnt vmcnt(0)
	ds_write_b128 v166, v[144:147]
	ds_write_b128 v167, v[148:151]
	ds_write_b128 v166, v[152:155] offset:8704
	ds_write_b128 v167, v[156:159] offset:9216
	v_mov_b32_e32 v0, 0
	v_mov_b32_e32 v1, 0
	v_mov_b32_e32 v2, 0
	v_mov_b32_e32 v3, 0
	v_mov_b32_e32 v4, 0
	v_mov_b32_e32 v5, 0
	v_mov_b32_e32 v6, 0
	v_mov_b32_e32 v7, 0
	v_mov_b32_e32 v8, 0
	v_mov_b32_e32 v9, 0
	v_mov_b32_e32 v10, 0
	v_mov_b32_e32 v11, 0
	v_mov_b32_e32 v12, 0
	v_mov_b32_e32 v13, 0
	v_mov_b32_e32 v14, 0
	v_mov_b32_e32 v15, 0
	v_mov_b32_e32 v16, 0
	v_mov_b32_e32 v17, 0
	v_mov_b32_e32 v18, 0
	v_mov_b32_e32 v19, 0
	v_mov_b32_e32 v20, 0
	v_mov_b32_e32 v21, 0
	v_mov_b32_e32 v22, 0
	v_mov_b32_e32 v23, 0
	v_mov_b32_e32 v24, 0
	v_mov_b32_e32 v25, 0
	v_mov_b32_e32 v26, 0
	v_mov_b32_e32 v27, 0
	v_mov_b32_e32 v28, 0
	v_mov_b32_e32 v29, 0
	v_mov_b32_e32 v30, 0
	v_mov_b32_e32 v31, 0
	v_mov_b32_e32 v32, 0
	v_mov_b32_e32 v33, 0
	v_mov_b32_e32 v34, 0
	v_mov_b32_e32 v35, 0
	v_mov_b32_e32 v36, 0
	v_mov_b32_e32 v37, 0
	v_mov_b32_e32 v38, 0
	v_mov_b32_e32 v39, 0
	v_mov_b32_e32 v40, 0
	v_mov_b32_e32 v41, 0
	v_mov_b32_e32 v42, 0
	v_mov_b32_e32 v43, 0
	v_mov_b32_e32 v44, 0
	v_mov_b32_e32 v45, 0
	v_mov_b32_e32 v46, 0
	v_mov_b32_e32 v47, 0
	v_mov_b32_e32 v48, 0
	v_mov_b32_e32 v49, 0
	v_mov_b32_e32 v50, 0
	v_mov_b32_e32 v51, 0
	v_mov_b32_e32 v52, 0
	v_mov_b32_e32 v53, 0
	v_mov_b32_e32 v54, 0
	v_mov_b32_e32 v55, 0
	v_mov_b32_e32 v56, 0
	v_mov_b32_e32 v57, 0
	v_mov_b32_e32 v58, 0
	v_mov_b32_e32 v59, 0
	v_mov_b32_e32 v60, 0
	v_mov_b32_e32 v61, 0
	v_mov_b32_e32 v62, 0
	v_mov_b32_e32 v63, 0
	v_mov_b32_e32 v173, 0
	s_mov_b32 s9, 0
	s_mov_b32 s10, 0
	s_mov_b32 s11, 0x8c00
	s_waitcnt lgkmcnt(0)
	s_barrier
; #define LAS __attribute__((address_space(3)))
; #define LDS_WAIT() asm volatile("s_waitcnt lgkmcnt(0)" ::: "memory")
; __device__ __forceinline__ void dsa_unit(const bf16* QB, const int* SEL, bf16* AO, int b, int kvh, int t, LAS unsigned char* wl, int lane) {
;     ...
;     for (int kb = 0; kb < 8; ++kb) {
; #pragma unroll
;         for (int i = 0; i < 8; ++i) *(LAS bf16x8*)(kdst + (4 * i) * 272) = kr[kb % 3][i];
;         if (kb + 3 < 8) {
; #pragma unroll
;             for (int i = 0; i < 8; ++i) kr[kb % 3][i] = *(const bf16x8*)(kg + (size_t)il[32 * (kb + 3) + 4 * i + r4] * NBP);
;         }
;         LDS_WAIT();
;         f32x4v a0 = {0.f, 0.f, 0.f, 0.f}, a1 = {0.f, 0.f, 0.f, 0.f};
; #pragma unroll
;         for (int ks = 0; ks < 4; ++ks) { const bf16x8 b0 = *(const LAS bf16x8*)(kfb + 64 * ks), b1 = *(const LAS bf16x8*)(kfb + 16 * 272 + 64 * ks);
;             a0 = __builtin_amdgcn_mfma_f32_16x16x32_bf16(qf[ks], b0, a0, 0, 0, 0); a1 = __builtin_amdgcn_mfma_f32_16x16x32_bf16(qf[ks], b1, a1, 0, 0, 0); }
;         LDS_WAIT();
;         const int bk = t5_bucket(sidx[kb] - t);
;         const bool valid = (32 * kb + n) < nsel;
; #pragma unroll
;         for (int g = 0; g < 4; ++g) { const float raw = upper ? a1[g] : a0[g]; const float v = valid ? raw + bl[g * 32 + bk] : -__builtin_inff(); lg[kb][g] = v; mx[g] = __builtin_fmaxf(mx[g], v); }
.Ldsa_it:
	v_add_u32_e32 v168, s10, v164
	v_add_u32_e32 v169, s10, v165
	v_add_u32_e32 v170, s11, v166
	v_add_u32_e32 v171, s11, v167
	s_add_u32 s24, s9, 1
	s_cmp_lt_u32 s24, s8
	s_cbranch_scc0 .Ldsa_nold
	global_load_dwordx4 v[144:147], v[160:161], off
	global_load_dwordx4 v[148:151], v[160:161], off offset:1024
	global_load_dwordx4 v[152:155], v[162:163], off
	global_load_dwordx4 v[156:159], v[162:163], off offset:1024
	v_lshl_add_u64 v[160:161], v[160:161], 0, s[16:17]
	v_lshl_add_u64 v[162:163], v[162:163], 0, s[16:17]
.Ldsa_nold:
	s_lshl_b32 s20, s9, 6
	ds_read_b32 v174, v172 offset:0
	ds_read_b128 v[112:115], v168 offset:0
	ds_read_b128 v[116:119], v168 offset:32
	ds_read_b128 v[120:123], v168 offset:64
	ds_read_b128 v[124:127], v168 offset:96
	s_waitcnt lgkmcnt(3)
	v_mfma_f32_32x32x16_bf16 v[64:79], v[112:115], v[80:83], 0
	s_waitcnt lgkmcnt(2)
	v_mfma_f32_32x32x16_bf16 v[64:79], v[116:119], v[84:87], v[64:79]
	s_waitcnt lgkmcnt(1)
	v_mfma_f32_32x32x16_bf16 v[64:79], v[120:123], v[88:91], v[64:79]
	s_waitcnt lgkmcnt(0)
	v_mfma_f32_32x32x16_bf16 v[64:79], v[124:127], v[92:95], v[64:79]
	ds_read_b128 v[112:115], v168 offset:128
	ds_read_b128 v[116:119], v168 offset:160
	ds_read_b128 v[120:123], v168 offset:192
	ds_read_b128 v[124:127], v168 offset:224
	s_waitcnt lgkmcnt(3)
	v_mfma_f32_32x32x16_bf16 v[64:79], v[112:115], v[96:99], v[64:79]
	s_waitcnt lgkmcnt(2)
	v_mfma_f32_32x32x16_bf16 v[64:79], v[116:119], v[100:103], v[64:79]
	s_waitcnt lgkmcnt(1)
	v_mfma_f32_32x32x16_bf16 v[64:79], v[120:123], v[104:107], v[64:79]
	s_waitcnt lgkmcnt(0)
	v_mfma_f32_32x32x16_bf16 v[64:79], v[124:127], v[108:111], v[64:79]
	ds_read_b64_tr_b16 v[128:129], v169 offset:0
	ds_read_b64_tr_b16 v[130:131], v169 offset:1152
	ds_read_b64_tr_b16 v[132:133], v169 offset:64
	ds_read_b64_tr_b16 v[134:135], v169 offset:1216
	ds_read_b64_tr_b16 v[136:137], v169 offset:128
	ds_read_b64_tr_b16 v[138:139], v169 offset:1280
	ds_read_b64_tr_b16 v[140:141], v169 offset:192
	ds_read_b64_tr_b16 v[142:143], v169 offset:1344
	s_nop 3
	v_lshrrev_b32_e32 v174, v175, v174
	s_cmp_le_i32 s20, s19
	s_cbranch_scc0 .Ldsa_near0
	v_add_f32_e32 v64, v176, v64
	v_add_f32_e32 v65, v176, v65
	v_add_f32_e32 v66, v176, v66
	v_add_f32_e32 v67, v176, v67
	v_add_f32_e32 v68, v176, v68
	v_add_f32_e32 v69, v176, v69
	v_add_f32_e32 v70, v176, v70
	v_add_f32_e32 v71, v176, v71
	v_add_f32_e32 v72, v176, v72
	v_add_f32_e32 v73, v176, v73
	v_add_f32_e32 v74, v176, v74
	v_add_f32_e32 v75, v176, v75
	v_add_f32_e32 v76, v176, v76
	v_add_f32_e32 v77, v176, v77
	v_add_f32_e32 v78, v176, v78
	v_add_f32_e32 v79, v176, v79
	s_branch .Ldsa_join0
.Ldsa_near0:
	s_lshl_b32 s26, s20, 2
	v_add_u32_e32 v179, s26, v177
	ds_read_b32 v112, v179 offset:0
	ds_read_b32 v113, v179 offset:4
	ds_read_b32 v114, v179 offset:8
	ds_read_b32 v115, v179 offset:12
	ds_read_b32 v116, v179 offset:16
	ds_read_b32 v117, v179 offset:20
	ds_read_b32 v118, v179 offset:24
	ds_read_b32 v119, v179 offset:28
	ds_read_b32 v120, v179 offset:64
	ds_read_b32 v121, v179 offset:68
	ds_read_b32 v122, v179 offset:72
	ds_read_b32 v123, v179 offset:76
	ds_read_b32 v124, v179 offset:80
	ds_read_b32 v125, v179 offset:84
	ds_read_b32 v126, v179 offset:88
	ds_read_b32 v127, v179 offset:92
	s_waitcnt lgkmcnt(0)
	v_add_f32_e32 v64, v112, v64
	v_add_f32_e32 v65, v113, v65
	v_add_f32_e32 v66, v114, v66
	v_add_f32_e32 v67, v115, v67
	v_add_f32_e32 v68, v116, v68
	v_add_f32_e32 v69, v117, v69
	v_add_f32_e32 v70, v118, v70
	v_add_f32_e32 v71, v119, v71
	v_add_f32_e32 v72, v120, v72
	v_add_f32_e32 v73, v121, v73
	v_add_f32_e32 v74, v122, v74
	v_add_f32_e32 v75, v123, v75
	v_add_f32_e32 v76, v124, v76
	v_add_f32_e32 v77, v125, v77
	v_add_f32_e32 v78, v126, v78
	v_add_f32_e32 v79, v127, v79
; __device__ __forceinline__ void dsa_unit(const bf16* QB, const int* SEL, bf16* AO, int b, int kvh, int t, LAS unsigned char* wl, int lane) {
;     ...
;         f32x4v a0 = {0.f, 0.f, 0.f, 0.f}, a1 = {0.f, 0.f, 0.f, 0.f};
; #pragma unroll
;         for (int ks = 0; ks < 4; ++ks) { const bf16x8 b0 = *(const LAS bf16x8*)(kfb + 64 * ks), b1 = *(const LAS bf16x8*)(kfb + 16 * 272 + 64 * ks);
;             a0 = __builtin_amdgcn_mfma_f32_16x16x32_bf16(qf[ks], b0, a0, 0, 0, 0); a1 = __builtin_amdgcn_mfma_f32_16x16x32_bf16(qf[ks], b1, a1, 0, 0, 0); }
;         LDS_WAIT();
;         const int bk = t5_bucket(sidx[kb] - t);
;         const bool valid = (32 * kb + n) < nsel;
; #pragma unroll
;         for (int g = 0; g < 4; ++g) { const float raw = upper ? a1[g] : a0[g]; const float v = valid ? raw + bl[g * 32 + bk] : -__builtin_inff(); lg[kb][g] = v; mx[g] = __builtin_fmaxf(mx[g], v); }
;     }
;     bf16x8 vr[3][8];
; #pragma unroll
;     for (int pb = 0; pb < 3; ++pb)
; #pragma unroll
;         for (int i = 0; i < 8; ++i) vr[pb][i] = *(const bf16x8*)(vg + (size_t)il[32 * pb + 4 * i + r4] * NBP);
; #pragma unroll
;     for (int g = 0; g < 4; ++g) {
;         float m = mx[g];
;         m = __builtin_fmaxf(m, __shfl_xor(m, 1)); m = __builtin_fmaxf(m, __shfl_xor(m, 2)); m = __builtin_fmaxf(m, __shfl_xor(m, 4)); m = __builtin_fmaxf(m, __shfl_xor(m, 8)); m = __builtin_fmaxf(m, __shfl_xor(m, 16));
;         float s = 0.f;
; #pragma unroll
;         for (int kb = 0; kb < 8; ++kb) { const float e = __builtin_amdgcn_exp2f(lg[kb][g] - m); lg[kb][g] = e; s += e; }
;         s += __shfl_xor(s, 1); s += __shfl_xor(s, 2); s += __shfl_xor(s, 4); s += __shfl_xor(s, 8); s += __shfl_xor(s, 16);
;         const float inv = 1.0f / s;
; #pragma unroll
;         for (int kb = 0; kb < 8; ++kb) if ((kb >> 2) == hi) pT[g * 256 + 32 * kb + n] = (bf16)(pk2(lg[kb][g] * inv, 0.f) & 0xffffu);
;     }
;     f32x4v o[8];
; #pragma unroll
;     for (int c = 0; c < 8; ++c) o[c] = (f32x4v){0.f, 0.f, 0.f, 0.f};
;     const LAS unsigned char* vtb = buf + (8 * kq + (l15 >> 2)) * 288 + (lane & 3) * 8;
;     LAS unsigned char* vdst = buf + r4 * 288 + c16 * 16;
;     const LAS bf16* pfp = pT + (l15 & 3) * 256 + 8 * kq;
; #pragma unroll
;     for (int ch = 0; ch < 8; ++ch) {
; #pragma unroll
;         for (int i = 0; i < 8; ++i) *(LAS bf16x8*)(vdst + (4 * i) * 288) = vr[ch % 3][i];
;         if (ch + 3 < 8) {
.Ldsa_join0:
	v_bfe_i32 v112, v174, 0, 1
	v_bfe_i32 v113, v174, 1, 1
	v_bfe_i32 v114, v174, 2, 1
	v_bfe_i32 v115, v174, 3, 1
	v_bfe_i32 v116, v174, 4, 1
	v_bfe_i32 v117, v174, 5, 1
	v_bfe_i32 v118, v174, 6, 1
	v_bfe_i32 v119, v174, 7, 1
	v_bfe_i32 v120, v174, 16, 1
	v_bfe_i32 v121, v174, 17, 1
	v_bfe_i32 v122, v174, 18, 1
	v_bfe_i32 v123, v174, 19, 1
	v_bfe_i32 v124, v174, 20, 1
	v_bfe_i32 v125, v174, 21, 1
	v_bfe_i32 v126, v174, 22, 1
	v_bfe_i32 v127, v174, 23, 1
	v_exp_f32_e32 v64, v64
	v_exp_f32_e32 v65, v65
	v_exp_f32_e32 v66, v66
	v_exp_f32_e32 v67, v67
	v_exp_f32_e32 v68, v68
	v_exp_f32_e32 v69, v69
	v_exp_f32_e32 v70, v70
	v_exp_f32_e32 v71, v71
	v_exp_f32_e32 v72, v72
	v_exp_f32_e32 v73, v73
	v_exp_f32_e32 v74, v74
	v_exp_f32_e32 v75, v75
	v_exp_f32_e32 v76, v76
	v_exp_f32_e32 v77, v77
	v_exp_f32_e32 v78, v78
	v_exp_f32_e32 v79, v79
	s_nop 0
	v_and_b32_e32 v64, v112, v64
	v_and_b32_e32 v65, v113, v65
	v_and_b32_e32 v66, v114, v66
	v_and_b32_e32 v67, v115, v67
	v_and_b32_e32 v68, v116, v68
	v_and_b32_e32 v69, v117, v69
	v_and_b32_e32 v70, v118, v70
	v_and_b32_e32 v71, v119, v71
	v_and_b32_e32 v72, v120, v72
	v_and_b32_e32 v73, v121, v73
	v_and_b32_e32 v74, v122, v74
	v_and_b32_e32 v75, v123, v75
	v_and_b32_e32 v76, v124, v76
	v_and_b32_e32 v77, v125, v77
	v_and_b32_e32 v78, v126, v78
	v_and_b32_e32 v79, v127, v79
	v_add_f32_e32 v173, v173, v64
	v_add_f32_e32 v173, v173, v65
	v_add_f32_e32 v173, v173, v66
	v_add_f32_e32 v173, v173, v67
	v_add_f32_e32 v173, v173, v68
	v_add_f32_e32 v173, v173, v69
	v_add_f32_e32 v173, v173, v70
	v_add_f32_e32 v173, v173, v71
	v_add_f32_e32 v173, v173, v72
	v_add_f32_e32 v173, v173, v73
	v_add_f32_e32 v173, v173, v74
	v_add_f32_e32 v173, v173, v75
	v_add_f32_e32 v173, v173, v76
	v_add_f32_e32 v173, v173, v77
	v_add_f32_e32 v173, v173, v78
	v_add_f32_e32 v173, v173, v79
	v_cvt_pk_bf16_f32 v64, v64, v65
	v_cvt_pk_bf16_f32 v65, v66, v67
	v_cvt_pk_bf16_f32 v66, v68, v69
	v_cvt_pk_bf16_f32 v67, v70, v71
	v_cvt_pk_bf16_f32 v68, v72, v73
	v_cvt_pk_bf16_f32 v69, v74, v75
	v_cvt_pk_bf16_f32 v70, v76, v77
	v_cvt_pk_bf16_f32 v71, v78, v79
	s_waitcnt lgkmcnt(0)
	s_nop 1
	v_mfma_f32_32x32x16_bf16 v[0:15], v[64:67], v[128:131], v[0:15]
	v_mfma_f32_32x32x16_bf16 v[16:31], v[64:67], v[132:135], v[16:31]
	v_mfma_f32_32x32x16_bf16 v[32:47], v[64:67], v[136:139], v[32:47]
	v_mfma_f32_32x32x16_bf16 v[48:63], v[64:67], v[140:143], v[48:63]
	ds_read_b64_tr_b16 v[128:129], v169 offset:4608
	ds_read_b64_tr_b16 v[130:131], v169 offset:5760
	ds_read_b64_tr_b16 v[132:133], v169 offset:4672
	ds_read_b64_tr_b16 v[134:135], v169 offset:5824
	ds_read_b64_tr_b16 v[136:137], v169 offset:4736
	ds_read_b64_tr_b16 v[138:139], v169 offset:5888
	ds_read_b64_tr_b16 v[140:141], v169 offset:4800
	ds_read_b64_tr_b16 v[142:143], v169 offset:5952
	s_waitcnt lgkmcnt(0)
	v_mfma_f32_32x32x16_bf16 v[0:15], v[68:71], v[128:131], v[0:15]
	v_mfma_f32_32x32x16_bf16 v[16:31], v[68:71], v[132:135], v[16:31]
	v_mfma_f32_32x32x16_bf16 v[32:47], v[68:71], v[136:139], v[32:47]
	v_mfma_f32_32x32x16_bf16 v[48:63], v[68:71], v[140:143], v[48:63]
	s_add_u32 s20, s20, 32
	ds_read_b32 v174, v172 offset:4
	ds_read_b128 v[112:115], v168 offset:8704
	ds_read_b128 v[116:119], v168 offset:8736
	ds_read_b128 v[120:123], v168 offset:8768
	ds_read_b128 v[124:127], v168 offset:8800
	s_waitcnt lgkmcnt(3)
	v_mfma_f32_32x32x16_bf16 v[64:79], v[112:115], v[80:83], 0
	s_waitcnt lgkmcnt(2)
	v_mfma_f32_32x32x16_bf16 v[64:79], v[116:119], v[84:87], v[64:79]
	s_waitcnt lgkmcnt(1)
	v_mfma_f32_32x32x16_bf16 v[64:79], v[120:123], v[88:91], v[64:79]
	s_waitcnt lgkmcnt(0)
	v_mfma_f32_32x32x16_bf16 v[64:79], v[124:127], v[92:95], v[64:79]
	ds_read_b128 v[112:115], v168 offset:8832
	ds_read_b128 v[116:119], v168 offset:8864
	ds_read_b128 v[120:123], v168 offset:8896
	ds_read_b128 v[124:127], v168 offset:8928
	s_waitcnt lgkmcnt(3)
	v_mfma_f32_32x32x16_bf16 v[64:79], v[112:115], v[96:99], v[64:79]
	s_waitcnt lgkmcnt(2)
	v_mfma_f32_32x32x16_bf16 v[64:79], v[116:119], v[100:103], v[64:79]
	s_waitcnt lgkmcnt(1)
	v_mfma_f32_32x32x16_bf16 v[64:79], v[120:123], v[104:107], v[64:79]
	s_waitcnt lgkmcnt(0)
	v_mfma_f32_32x32x16_bf16 v[64:79], v[124:127], v[108:111], v[64:79]
	ds_read_b64_tr_b16 v[128:129], v169 offset:9216
	ds_read_b64_tr_b16 v[130:131], v169 offset:10368
	ds_read_b64_tr_b16 v[132:133], v169 offset:9280
	ds_read_b64_tr_b16 v[134:135], v169 offset:10432
	ds_read_b64_tr_b16 v[136:137], v169 offset:9344
	ds_read_b64_tr_b16 v[138:139], v169 offset:10496
	ds_read_b64_tr_b16 v[140:141], v169 offset:9408
	ds_read_b64_tr_b16 v[142:143], v169 offset:10560
	s_nop 3
	v_lshrrev_b32_e32 v174, v175, v174
	s_cmp_le_i32 s20, s19
	s_cbranch_scc0 .Ldsa_near1
	v_add_f32_e32 v64, v176, v64
	v_add_f32_e32 v65, v176, v65
	v_add_f32_e32 v66, v176, v66
	v_add_f32_e32 v67, v176, v67
	v_add_f32_e32 v68, v176, v68
	v_add_f32_e32 v69, v176, v69
	v_add_f32_e32 v70, v176, v70
	v_add_f32_e32 v71, v176, v71
	v_add_f32_e32 v72, v176, v72
	v_add_f32_e32 v73, v176, v73
	v_add_f32_e32 v74, v176, v74
	v_add_f32_e32 v75, v176, v75
	v_add_f32_e32 v76, v176, v76
	v_add_f32_e32 v77, v176, v77
	v_add_f32_e32 v78, v176, v78
	v_add_f32_e32 v79, v176, v79
	s_branch .Ldsa_join1

; #define LAS __attribute__((address_space(3)))
; __device__ __forceinline__ unsigned pk2(float lo, float hi) { return pg8::cvt_pk_bf16(lo, hi); }
; #define LDS_WAIT() asm volatile("s_waitcnt lgkmcnt(0)" ::: "memory")
; __device__ __forceinline__ void dsa_unit(const bf16* QB, const int* SEL, bf16* AO, int b, int kvh, int t, LAS unsigned char* wl, int lane) {
;     ...
;     for (int g = 0; g < 4; ++g) {
;         float m = mx[g];
;         m = __builtin_fmaxf(m, __shfl_xor(m, 1)); m = __builtin_fmaxf(m, __shfl_xor(m, 2)); m = __builtin_fmaxf(m, __shfl_xor(m, 4)); m = __builtin_fmaxf(m, __shfl_xor(m, 8)); m = __builtin_fmaxf(m, __shfl_xor(m, 16));
;         float s = 0.f;
; #pragma unroll
;         for (int kb = 0; kb < 8; ++kb) { const float e = __builtin_amdgcn_exp2f(lg[kb][g] - m); lg[kb][g] = e; s += e; }
;         s += __shfl_xor(s, 1); s += __shfl_xor(s, 2); s += __shfl_xor(s, 4); s += __shfl_xor(s, 8); s += __shfl_xor(s, 16);
;         const float inv = 1.0f / s;
; #pragma unroll
;         for (int kb = 0; kb < 8; ++kb) if ((kb >> 2) == hi) pT[g * 256 + 32 * kb + n] = (bf16)(pk2(lg[kb][g] * inv, 0.f) & 0xffffu);
;     }
;     f32x4v o[8];
; #pragma unroll
;     for (int c = 0; c < 8; ++c) o[c] = (f32x4v){0.f, 0.f, 0.f, 0.f};
;     const LAS unsigned char* vtb = buf + (8 * kq + (l15 >> 2)) * 288 + (lane & 3) * 8;
;     LAS unsigned char* vdst = buf + r4 * 288 + c16 * 16;
;     const LAS bf16* pfp = pT + (l15 & 3) * 256 + 8 * kq;
; #pragma unroll
;     for (int ch = 0; ch < 8; ++ch) {
; #pragma unroll
;         for (int i = 0; i < 8; ++i) *(LAS bf16x8*)(vdst + (4 * i) * 288) = vr[ch % 3][i];
;         if (ch + 3 < 8) {
; #pragma unroll
;             for (int i = 0; i < 8; ++i) vr[ch % 3][i] = *(const bf16x8*)(vg + (size_t)il[32 * (ch + 3) + 4 * i + r4] * NBP);
;         }
;         const bf16x8 pf = *(const LAS bf16x8*)(pfp + 32 * ch);
;         LDS_WAIT();
; #pragma unroll
;         for (int c = 0; c < 8; ++c) {
;             const s16x4 lo = vtr(vtb + c * 32), hh = vtr(vtb + 4 * 288 + c * 32);
;             o[c] = __builtin_amdgcn_mfma_f32_16x16x32_bf16(pf, (bf16x8){lo[0], lo[1], lo[2], lo[3], hh[0], hh[1], hh[2], hh[3]}, o[c], 0, 0, 0);
;         }
;         LDS_WAIT();
;     }
;     bf16* op = AO + row * D + (kvh * 4) * 128 + 16 * kq + l15;
.Ldsa_join1:
	v_bfe_i32 v112, v174, 0, 1
	v_bfe_i32 v113, v174, 1, 1
	v_bfe_i32 v114, v174, 2, 1
	v_bfe_i32 v115, v174, 3, 1
	v_bfe_i32 v116, v174, 4, 1
	v_bfe_i32 v117, v174, 5, 1
	v_bfe_i32 v118, v174, 6, 1
	v_bfe_i32 v119, v174, 7, 1
	v_bfe_i32 v120, v174, 16, 1
	v_bfe_i32 v121, v174, 17, 1
	v_bfe_i32 v122, v174, 18, 1
	v_bfe_i32 v123, v174, 19, 1
	v_bfe_i32 v124, v174, 20, 1
	v_bfe_i32 v125, v174, 21, 1
	v_bfe_i32 v126, v174, 22, 1
	v_bfe_i32 v127, v174, 23, 1
	v_exp_f32_e32 v64, v64
	v_exp_f32_e32 v65, v65
	v_exp_f32_e32 v66, v66
	v_exp_f32_e32 v67, v67
	v_exp_f32_e32 v68, v68
	v_exp_f32_e32 v69, v69
	v_exp_f32_e32 v70, v70
	v_exp_f32_e32 v71, v71
	v_exp_f32_e32 v72, v72
	v_exp_f32_e32 v73, v73
	v_exp_f32_e32 v74, v74
	v_exp_f32_e32 v75, v75
	v_exp_f32_e32 v76, v76
	v_exp_f32_e32 v77, v77
	v_exp_f32_e32 v78, v78
	v_exp_f32_e32 v79, v79
	s_nop 0
	v_and_b32_e32 v64, v112, v64
	v_and_b32_e32 v65, v113, v65
	v_and_b32_e32 v66, v114, v66
	v_and_b32_e32 v67, v115, v67
	v_and_b32_e32 v68, v116, v68
	v_and_b32_e32 v69, v117, v69
	v_and_b32_e32 v70, v118, v70
	v_and_b32_e32 v71, v119, v71
	v_and_b32_e32 v72, v120, v72
	v_and_b32_e32 v73, v121, v73
	v_and_b32_e32 v74, v122, v74
	v_and_b32_e32 v75, v123, v75
	v_and_b32_e32 v76, v124, v76
	v_and_b32_e32 v77, v125, v77
	v_and_b32_e32 v78, v126, v78
	v_and_b32_e32 v79, v127, v79
	v_add_f32_e32 v173, v173, v64
	v_add_f32_e32 v173, v173, v65
	v_add_f32_e32 v173, v173, v66
	v_add_f32_e32 v173, v173, v67
	v_add_f32_e32 v173, v173, v68
	v_add_f32_e32 v173, v173, v69
	v_add_f32_e32 v173, v173, v70
	v_add_f32_e32 v173, v173, v71
	v_add_f32_e32 v173, v173, v72
	v_add_f32_e32 v173, v173, v73
	v_add_f32_e32 v173, v173, v74
	v_add_f32_e32 v173, v173, v75
	v_add_f32_e32 v173, v173, v76
	v_add_f32_e32 v173, v173, v77
	v_add_f32_e32 v173, v173, v78
	v_add_f32_e32 v173, v173, v79
	v_cvt_pk_bf16_f32 v64, v64, v65
	v_cvt_pk_bf16_f32 v65, v66, v67
	v_cvt_pk_bf16_f32 v66, v68, v69
	v_cvt_pk_bf16_f32 v67, v70, v71
	v_cvt_pk_bf16_f32 v68, v72, v73
	v_cvt_pk_bf16_f32 v69, v74, v75
	v_cvt_pk_bf16_f32 v70, v76, v77
	v_cvt_pk_bf16_f32 v71, v78, v79
	s_waitcnt lgkmcnt(0)
	s_nop 1
	v_mfma_f32_32x32x16_bf16 v[0:15], v[64:67], v[128:131], v[0:15]
	v_mfma_f32_32x32x16_bf16 v[16:31], v[64:67], v[132:135], v[16:31]
	v_mfma_f32_32x32x16_bf16 v[32:47], v[64:67], v[136:139], v[32:47]
	v_mfma_f32_32x32x16_bf16 v[48:63], v[64:67], v[140:143], v[48:63]
	ds_read_b64_tr_b16 v[128:129], v169 offset:13824
	ds_read_b64_tr_b16 v[130:131], v169 offset:14976
	ds_read_b64_tr_b16 v[132:133], v169 offset:13888
	ds_read_b64_tr_b16 v[134:135], v169 offset:15040
	ds_read_b64_tr_b16 v[136:137], v169 offset:13952
	ds_read_b64_tr_b16 v[138:139], v169 offset:15104
	ds_read_b64_tr_b16 v[140:141], v169 offset:14016
	ds_read_b64_tr_b16 v[142:143], v169 offset:15168
	s_waitcnt lgkmcnt(0)
	v_mfma_f32_32x32x16_bf16 v[0:15], v[68:71], v[128:131], v[0:15]
	v_mfma_f32_32x32x16_bf16 v[16:31], v[68:71], v[132:135], v[16:31]
	v_mfma_f32_32x32x16_bf16 v[32:47], v[68:71], v[136:139], v[32:47]
	v_mfma_f32_32x32x16_bf16 v[48:63], v[68:71], v[140:143], v[48:63]
	s_cmp_lt_u32 s24, s8
	s_cbranch_scc0 .Ldsa_nost
	s_waitcnt vmcnt(0)
	ds_write_b128 v170, v[144:147]
	ds_write_b128 v171, v[148:151]
	ds_write_b128 v170, v[152:155] offset:8704
	ds_write_b128 v171, v[156:159] offset:9216
.Ldsa_nost:
	s_waitcnt lgkmcnt(0)
	s_barrier
	s_mov_b32 s25, s10
	s_mov_b32 s10, s11
	s_mov_b32 s11, s25
	v_add_u32_e32 v172, 8, v172
	s_mov_b32 s9, s24
	s_cmp_lt_u32 s9, s8
	s_cbranch_scc1 .Ldsa_it
	v_xor_b32_e32 v178, 32, v206
	v_lshlrev_b32_e32 v178, 2, v178
	ds_bpermute_b32 v179, v178, v173
	s_waitcnt lgkmcnt(0)
	v_add_f32_e32 v173, v173, v179
	v_rcp_f32_e32 v173, v173
	s_nop 0
	v_and_b32_e32 v178, 31, v206
	v_lshlrev_b32_e32 v178, 2, v178
	s_lshl_b32 s24, s0, 7
	s_add_u32 s24, s24, 0x1a000
	v_add_u32_e32 v178, s24, v178
	ds_write_b32 v178, v173
	v_lshl_add_u32 v179, v175, 1, s24
	s_waitcnt lgkmcnt(0)
	ds_read_b128 v[112:115], v179 offset:0
	ds_read_b128 v[116:119], v179 offset:32
	ds_read_b128 v[120:123], v179 offset:64
	ds_read_b128 v[124:127], v179 offset:96
	s_lshl_b32 s24, s0, 3
	s_add_u32 s24, s24, s7
	s_add_u32 s24, s24, s4
	s_lshr_b32 s25, s24, 20
	s_lshl_b32 s24, s24, 12
	s_add_u32 s24, s24, s67
	s_addc_u32 s25, s25, s85
	s_lshl_b32 s26, s5, 10
	s_add_u32 s24, s24, s26
	s_addc_u32 s25, s25, 0
	v_and_b32_e32 v178, 31, v206
	v_lshlrev_b32_e32 v178, 1, v178
	v_lshl_add_u32 v182, v175, 9, v178
	v_lshl_add_u64 v[144:145], s[24:25], 0, v[182:183]
	s_movk_i32 s26, 0x2000
	s_mov_b32 s27, 0
	v_lshl_add_u64 v[146:147], v[144:145], 0, s[26:27]
	v_lshl_add_u64 v[148:149], v[146:147], 0, s[26:27]
	v_lshl_add_u64 v[150:151], v[148:149], 0, s[26:27]
	s_waitcnt lgkmcnt(0)
; __device__ __forceinline__ unsigned pk2(float lo, float hi) { return pg8::cvt_pk_bf16(lo, hi); }
; __device__ __forceinline__ void dsa_unit(const bf16* QB, const int* SEL, bf16* AO, int b, int kvh, int t, LAS unsigned char* wl, int lane) {
;     ...
;     bf16* op = AO + row * D + (kvh * 4) * 128 + 16 * kq + l15;
; #pragma unroll
;     for (int i = 0; i < 2; ++i)
; #pragma unroll
;         for (int g = 0; g < 4; ++g) {
;             const float v = (kq == 0) ? o[4 * i][g] : (kq == 1) ? o[4 * i + 1][g] : (kq == 2) ? o[4 * i + 2][g] : o[4 * i + 3][g];
;             op[g * 128 + 64 * i] = (bf16)(pk2(v, 0.f) & 0xffffu);
;         }
	v_mul_f32_e32 v64, v0, v112
	v_mul_f32_e32 v65, v1, v113
	v_mul_f32_e32 v66, v2, v114
	v_mul_f32_e32 v67, v3, v115
	v_mul_f32_e32 v68, v4, v116
	v_mul_f32_e32 v69, v5, v117
	v_mul_f32_e32 v70, v6, v118
	v_mul_f32_e32 v71, v7, v119
	v_mul_f32_e32 v72, v8, v120
	v_mul_f32_e32 v73, v9, v121
	v_mul_f32_e32 v74, v10, v122
	v_mul_f32_e32 v75, v11, v123
	v_mul_f32_e32 v76, v12, v124
	v_mul_f32_e32 v77, v13, v125
	v_mul_f32_e32 v78, v14, v126
	v_mul_f32_e32 v79, v15, v127
	v_cvt_pk_bf16_f32 v64, v64, v183
	v_cvt_pk_bf16_f32 v65, v65, v183
	v_cvt_pk_bf16_f32 v66, v66, v183
	v_cvt_pk_bf16_f32 v67, v67, v183
	v_cvt_pk_bf16_f32 v68, v68, v183
	v_cvt_pk_bf16_f32 v69, v69, v183
	v_cvt_pk_bf16_f32 v70, v70, v183
	v_cvt_pk_bf16_f32 v71, v71, v183
	v_cvt_pk_bf16_f32 v72, v72, v183
	v_cvt_pk_bf16_f32 v73, v73, v183
	v_cvt_pk_bf16_f32 v74, v74, v183
	v_cvt_pk_bf16_f32 v75, v75, v183
	v_cvt_pk_bf16_f32 v76, v76, v183
	v_cvt_pk_bf16_f32 v77, v77, v183
	v_cvt_pk_bf16_f32 v78, v78, v183
	v_cvt_pk_bf16_f32 v79, v79, v183
	global_store_short v[144:145], v64, off offset:0
	global_store_short v[144:145], v65, off offset:256
	global_store_short v[144:145], v66, off offset:512
	global_store_short v[144:145], v67, off offset:768
	global_store_short v[146:147], v68, off offset:0
	global_store_short v[146:147], v69, off offset:256
	global_store_short v[146:147], v70, off offset:512
	global_store_short v[146:147], v71, off offset:768
	global_store_short v[148:149], v72, off offset:0
	global_store_short v[148:149], v73, off offset:256
	global_store_short v[148:149], v74, off offset:512
	global_store_short v[148:149], v75, off offset:768
	global_store_short v[150:151], v76, off offset:0
	global_store_short v[150:151], v77, off offset:256
	global_store_short v[150:151], v78, off offset:512
	global_store_short v[150:151], v79, off offset:768
	v_mul_f32_e32 v64, v16, v112
	v_mul_f32_e32 v65, v17, v113
	v_mul_f32_e32 v66, v18, v114
	v_mul_f32_e32 v67, v19, v115
	v_mul_f32_e32 v68, v20, v116
	v_mul_f32_e32 v69, v21, v117
	v_mul_f32_e32 v70, v22, v118
	v_mul_f32_e32 v71, v23, v119
	v_mul_f32_e32 v72, v24, v120
	v_mul_f32_e32 v73, v25, v121
	v_mul_f32_e32 v74, v26, v122
	v_mul_f32_e32 v75, v27, v123
	v_mul_f32_e32 v76, v28, v124
	v_mul_f32_e32 v77, v29, v125
	v_mul_f32_e32 v78, v30, v126
	v_mul_f32_e32 v79, v31, v127
	v_cvt_pk_bf16_f32 v64, v64, v183
	v_cvt_pk_bf16_f32 v65, v65, v183
	v_cvt_pk_bf16_f32 v66, v66, v183
	v_cvt_pk_bf16_f32 v67, v67, v183
	v_cvt_pk_bf16_f32 v68, v68, v183
	v_cvt_pk_bf16_f32 v69, v69, v183
	v_cvt_pk_bf16_f32 v70, v70, v183
	v_cvt_pk_bf16_f32 v71, v71, v183
	v_cvt_pk_bf16_f32 v72, v72, v183
	v_cvt_pk_bf16_f32 v73, v73, v183
	v_cvt_pk_bf16_f32 v74, v74, v183
	v_cvt_pk_bf16_f32 v75, v75, v183
	v_cvt_pk_bf16_f32 v76, v76, v183
	v_cvt_pk_bf16_f32 v77, v77, v183
	v_cvt_pk_bf16_f32 v78, v78, v183
	v_cvt_pk_bf16_f32 v79, v79, v183
	global_store_short v[144:145], v64, off offset:64
	global_store_short v[144:145], v65, off offset:320
	global_store_short v[144:145], v66, off offset:576
	global_store_short v[144:145], v67, off offset:832
	global_store_short v[146:147], v68, off offset:64
	global_store_short v[146:147], v69, off offset:320
	global_store_short v[146:147], v70, off offset:576
	global_store_short v[146:147], v71, off offset:832
	global_store_short v[148:149], v72, off offset:64
	global_store_short v[148:149], v73, off offset:320
	global_store_short v[148:149], v74, off offset:576
	global_store_short v[148:149], v75, off offset:832
	global_store_short v[150:151], v76, off offset:64
	global_store_short v[150:151], v77, off offset:320
	global_store_short v[150:151], v78, off offset:576
	global_store_short v[150:151], v79, off offset:832
	v_mul_f32_e32 v64, v32, v112
	v_mul_f32_e32 v65, v33, v113
	v_mul_f32_e32 v66, v34, v114
	v_mul_f32_e32 v67, v35, v115
	v_mul_f32_e32 v68, v36, v116
	v_mul_f32_e32 v69, v37, v117
	v_mul_f32_e32 v70, v38, v118
	v_mul_f32_e32 v71, v39, v119
	v_mul_f32_e32 v72, v40, v120
	v_mul_f32_e32 v73, v41, v121
	v_mul_f32_e32 v74, v42, v122
	v_mul_f32_e32 v75, v43, v123
	v_mul_f32_e32 v76, v44, v124
	v_mul_f32_e32 v77, v45, v125
	v_mul_f32_e32 v78, v46, v126
	v_mul_f32_e32 v79, v47, v127
; __device__ __forceinline__ unsigned pk2(float lo, float hi) { return pg8::cvt_pk_bf16(lo, hi); }
; __device__ __forceinline__ void dsa_unit(const bf16* QB, const int* SEL, bf16* AO, int b, int kvh, int t, LAS unsigned char* wl, int lane) {
;     ...
;     bf16* op = AO + row * D + (kvh * 4) * 128 + 16 * kq + l15;
; #pragma unroll
;     for (int i = 0; i < 2; ++i)
; #pragma unroll
;         for (int g = 0; g < 4; ++g) {
;             const float v = (kq == 0) ? o[4 * i][g] : (kq == 1) ? o[4 * i + 1][g] : (kq == 2) ? o[4 * i + 2][g] : o[4 * i + 3][g];
;             op[g * 128 + 64 * i] = (bf16)(pk2(v, 0.f) & 0xffffu);
;         }
; __global__ void __launch_bounds__(NWAVES * 64, 2) fwd_megakernel(Args args) {
;     ...
;                 for (int rep = 0; rep < REP_DSA; ++rep)
;                 if ((G & 7) == 0) { const int x = blockIdx.x & 7; const int nxw = (G >> 3) * NWAVES; const int wx = (blockIdx.x >> 3) * NWAVES + wave;
;                     for (int i = wx; i < 2 * SEQ; i += nxw) { const int combo = x + 8 * (i / SEQ);
;     ...
;  dsa_unit(QKV, SEL, AO, combo >> 2, combo & 3, i % SEQ, wl, lane);
;     ...
;  } }
	v_cvt_pk_bf16_f32 v64, v64, v183
	v_cvt_pk_bf16_f32 v65, v65, v183
	v_cvt_pk_bf16_f32 v66, v66, v183
	v_cvt_pk_bf16_f32 v67, v67, v183
	v_cvt_pk_bf16_f32 v68, v68, v183
	v_cvt_pk_bf16_f32 v69, v69, v183
	v_cvt_pk_bf16_f32 v70, v70, v183
	v_cvt_pk_bf16_f32 v71, v71, v183
	v_cvt_pk_bf16_f32 v72, v72, v183
	v_cvt_pk_bf16_f32 v73, v73, v183
	v_cvt_pk_bf16_f32 v74, v74, v183
	v_cvt_pk_bf16_f32 v75, v75, v183
	v_cvt_pk_bf16_f32 v76, v76, v183
	v_cvt_pk_bf16_f32 v77, v77, v183
	v_cvt_pk_bf16_f32 v78, v78, v183
	v_cvt_pk_bf16_f32 v79, v79, v183
	global_store_short v[144:145], v64, off offset:128
	global_store_short v[144:145], v65, off offset:384
	global_store_short v[144:145], v66, off offset:640
	global_store_short v[144:145], v67, off offset:896
	global_store_short v[146:147], v68, off offset:128
	global_store_short v[146:147], v69, off offset:384
	global_store_short v[146:147], v70, off offset:640
	global_store_short v[146:147], v71, off offset:896
	global_store_short v[148:149], v72, off offset:128
	global_store_short v[148:149], v73, off offset:384
	global_store_short v[148:149], v74, off offset:640
	global_store_short v[148:149], v75, off offset:896
	global_store_short v[150:151], v76, off offset:128
	global_store_short v[150:151], v77, off offset:384
	global_store_short v[150:151], v78, off offset:640
	global_store_short v[150:151], v79, off offset:896
	v_mul_f32_e32 v64, v48, v112
	v_mul_f32_e32 v65, v49, v113
	v_mul_f32_e32 v66, v50, v114
	v_mul_f32_e32 v67, v51, v115
	v_mul_f32_e32 v68, v52, v116
	v_mul_f32_e32 v69, v53, v117
	v_mul_f32_e32 v70, v54, v118
	v_mul_f32_e32 v71, v55, v119
	v_mul_f32_e32 v72, v56, v120
	v_mul_f32_e32 v73, v57, v121
	v_mul_f32_e32 v74, v58, v122
	v_mul_f32_e32 v75, v59, v123
	v_mul_f32_e32 v76, v60, v124
	v_mul_f32_e32 v77, v61, v125
	v_mul_f32_e32 v78, v62, v126
	v_mul_f32_e32 v79, v63, v127
	v_cvt_pk_bf16_f32 v64, v64, v183
	v_cvt_pk_bf16_f32 v65, v65, v183
	v_cvt_pk_bf16_f32 v66, v66, v183
	v_cvt_pk_bf16_f32 v67, v67, v183
	v_cvt_pk_bf16_f32 v68, v68, v183
	v_cvt_pk_bf16_f32 v69, v69, v183
	v_cvt_pk_bf16_f32 v70, v70, v183
	v_cvt_pk_bf16_f32 v71, v71, v183
	v_cvt_pk_bf16_f32 v72, v72, v183
	v_cvt_pk_bf16_f32 v73, v73, v183
	v_cvt_pk_bf16_f32 v74, v74, v183
	v_cvt_pk_bf16_f32 v75, v75, v183
	v_cvt_pk_bf16_f32 v76, v76, v183
	v_cvt_pk_bf16_f32 v77, v77, v183
	v_cvt_pk_bf16_f32 v78, v78, v183
	v_cvt_pk_bf16_f32 v79, v79, v183
	global_store_short v[144:145], v64, off offset:192
	global_store_short v[144:145], v65, off offset:448
	global_store_short v[144:145], v66, off offset:704
	global_store_short v[144:145], v67, off offset:960
	global_store_short v[146:147], v68, off offset:192
	global_store_short v[146:147], v69, off offset:448
	global_store_short v[146:147], v70, off offset:704
	global_store_short v[146:147], v71, off offset:960
	global_store_short v[148:149], v72, off offset:192
	global_store_short v[148:149], v73, off offset:448
	global_store_short v[148:149], v74, off offset:704
	global_store_short v[148:149], v75, off offset:960
	global_store_short v[150:151], v76, off offset:192
	global_store_short v[150:151], v77, off offset:448
	global_store_short v[150:151], v78, off offset:704
	global_store_short v[150:151], v79, off offset:960
	s_add_u32 s21, s21, 1
	s_cmp_lt_u32 s21, 2
	s_cbranch_scc1 .Ldsa_half
	s_add_u32 s3, s3, s2
	s_branch .Ldsa_unit
.Ldsa_done:
	s_branch .LBB0_999
.LBB0_999:
	s_add_i32 s35, s49, 3
	s_cmp_lt_i32 s35, s59
	s_waitcnt lgkmcnt(0)
	s_barrier
	s_cbranch_scc0 .LBB0_1030
	s_cmp_lg_u32 s22, s58
	s_mov_b64 s[0:1], -1
	s_cbranch_scc0 .LBB0_1017
	s_waitcnt vmcnt(0) lgkmcnt(0)
	s_add_i32 s8, s30, 1
	s_barrier
	s_mov_b64 s[0:1], exec
	v_readlane_b32 s2, v253, 38
	v_readlane_b32 s3, v253, 39
	s_and_b64 s[2:3], s[0:1], s[2:3]
	s_mov_b64 exec, s[2:3]
	s_cbranch_execz .LBB0_1016
	s_mov_b64 s[4:5], exec
	v_mbcnt_lo_u32_b32 v0, s4, 0
	v_mbcnt_hi_u32_b32 v0, s5, v0
	v_cmp_eq_u32_e32 vcc, 0, v0
	s_and_saveexec_b64 s[2:3], vcc
	s_cbranch_execz .LBB0_1004
	s_bcnt1_i32_b64 s4, s[4:5]
	v_mov_b32_e32 v1, s4
	v_readlane_b32 s4, v251, 33
	v_readlane_b32 s5, v251, 34
	s_nop 4
	global_atomic_add v1, v183, v1, s[4:5] offset:256 sc0
